# FFN_UP GEMM: first K-loop iteration of every unit peeled with C=0 inline constant in each accumulator's first MFMA; the 128 per-unit zeroing v_mov removed
# speedup vs baseline: 1.0160x; 1.0125x over previous
; #define PG8_STAGE(bufoff, gbase, voff) do { _Pragma("unroll") for (int _i = 0; _i < 2; ++_i) \
;         __builtin_amdgcn_global_load_lds((const unsigned*)((const char*)(gbase) + (voff)[_i]), (PG8_LAS unsigned*)(lds + (bufoff) + ldsw + _i * 8192), 16, 0, 0); } while (0)
; #define PG8_LDA(dst, b, h) do { _Pragma("unroll") for (int m = 0; m < 4; ++m) _Pragma("unroll") for (int k = 0; k < 2; ++k) dst[m][k] = *(const PG8_LAS bf16x8*)(lds + PG8_SA(b, h) + aoff + m * 2048 + k * 1024); } while (0)
; #define PG8_LDB(dst, b, h) do { _Pragma("unroll") for (int n = 0; n < 2; ++n) _Pragma("unroll") for (int k = 0; k < 2; ++k) dst[n][k] = *(const PG8_LAS bf16x8*)(lds + PG8_SB(b, h) + boff + n * 2048 + k * 1024); } while (0)
; #define PG8_MMA(ai, bj, At, Bt) do { __builtin_amdgcn_s_setprio(1); _Pragma("unroll") for (int m = 0; m < 4; ++m) _Pragma("unroll") for (int n = 0; n < 2; ++n) _Pragma("unroll") for (int k = 0; k < 2; ++k) \
;         acc[ai][bj][m][n] = __builtin_amdgcn_mfma_f32_16x16x32_bf16(Bt[n][k], At[m][k], acc[ai][bj][m][n], 0, 0, 0); __builtin_amdgcn_s_setprio(0); } while (0)
; #define PG8_WAIT_V(n) asm volatile("s_waitcnt vmcnt(" #n ")" ::: "memory")
; template <class Epi, class Sched, bool ALIGN_EPI = false, bool SP2 = false>
; __device__ __forceinline__ void gemm_phase(PG8_LAS unsigned char* lds, const Gemm g, const Sched& S, const Epi& E) {
;     ...
;         const char* nA = has_next ? (const char*)g.A + (size_t)nxt.pm * tstepA : cA; const char* nB = has_next ? (const char*)g.Bt + (size_t)nxt.pn * tstep : cB;
;         for (int t = 0; t < nt; t += 2) {
;             const bool last = (t == nt - 2);
;             const char* a1 = cA + (size_t)(t + 1) * kstep;
;             const char* a2 = last ? nA : cA + (size_t)(t + 2) * kstep; const char* b2 = last ? nB : cB + (size_t)(t + 2) * kstep;
;             const char* a3 = a2 + kstep; const char* b3 = b2 + kstep;
;             if (last && has_next) S.a_ready(nxt);
;             if constexpr (SP2) {
;             PG8_LDB(B0, 0, 0); PG8_LDB(B1, 0, 1); PG8_SCHED; PG8_LDA(At, 0, 0); PG8_STAGE(PG8_SA(1, 1), a1 + hstepA, voffA);
;             PG8_WAIT_V(8); PG8_WAIT_L(0); PG8_BAR; PG8_MMA(0, 0, At, B0); PG8_MMA(0, 1, At, B1); PG8_BAR; PG8_SCHED;
;             PG8_LDA(At, 0, 1); PG8_STAGE(PG8_SB(0, 0), b2, voffB); PG8_STAGE(PG8_SB(0, 1), b2 + hstep, voffB); PG8_STAGE(PG8_SA(0, 0), a2, voffA);
.LBB0_635:
	s_ashr_i32 s19, s18, 31
	s_lshl_b64 s[20:21], s[18:19], 19
	s_add_u32 s20, s30, s20
	s_addc_u32 s21, s31, s21
	s_and_b64 s[24:25], s[40:41], exec
	s_cselect_b32 s19, s21, s43
	s_cselect_b32 s55, s20, s42
	s_ashr_i32 s11, s10, 31
	s_lshl_b64 s[24:25], s[10:11], 19
	s_add_u32 s24, s51, s24
	s_addc_u32 s25, s52, s25
	s_and_b64 s[46:47], s[40:41], exec
	s_cselect_b32 s11, s25, s45
	s_cselect_b32 s56, s24, s44
	s_add_u32 s42, s42, 0x40080
	s_addc_u32 s43, s43, 0
	s_add_u32 s57, s44, 0x100
	s_addc_u32 s58, s45, 0
	s_mov_b32 s59, -2
	s_waitcnt vmcnt(0)
	s_add_u32 s44, s42, 0xfffc0080
	s_addc_u32 s45, s43, -1
	s_add_i32 s60, 0, 0x10000
	s_cmp_eq_u32 s59, 12
	s_cselect_b32 s47, s19, s45
	s_cselect_b32 s46, s55, s44
	v_add_u32_e32 v150, s60, v151
	s_cselect_b32 s45, s11, s58
	s_cselect_b32 s44, s56, s57
	s_add_i32 s62, 0, 0x14000
	ds_read_b128 v[146:149], v150
	ds_read_b128 v[152:155], v150 offset:1024
	ds_read_b128 v[162:165], v150 offset:2048
	ds_read_b128 v[166:169], v150 offset:3072
	v_add_u32_e32 v150, s62, v151
	ds_read_b128 v[170:173], v150
	ds_read_b128 v[174:177], v150 offset:1024
	ds_read_b128 v[178:181], v150 offset:2048
	ds_read_b128 v[182:185], v150 offset:3072
	v_lshl_add_u64 v[158:159], s[42:43], 0, v[142:143]
	s_add_i32 m0, s16, 0xc000
	ds_read_b128 v[186:189], v161
	ds_read_b128 v[190:193], v161 offset:1024
	ds_read_b128 v[198:201], v161 offset:2048
	ds_read_b128 v[202:205], v161 offset:3072
	ds_read_b128 v[206:209], v161 offset:4096
	ds_read_b128 v[210:213], v161 offset:5120
	ds_read_b128 v[214:217], v161 offset:6144
	ds_read_b128 v[218:221], v161 offset:7168
	global_load_lds_dwordx4 v[158:159], off
	v_lshl_add_u64 v[158:159], s[42:43], 0, v[144:145]
	s_add_i32 m0, s16, 0xe000
	s_nop 0
	global_load_lds_dwordx4 v[158:159], off
	s_waitcnt vmcnt(8)
	s_waitcnt lgkmcnt(0)
	s_barrier
	s_setprio 1
	s_waitcnt lgkmcnt(0)
	v_mfma_f32_16x16x32_bf16 v[132:135], v[146:149], v[186:189], 0
	v_mfma_f32_16x16x32_bf16 v[128:131], v[162:165], v[186:189], 0
	v_mfma_f32_16x16x32_bf16 v[116:119], v[146:149], v[198:201], 0
	v_mfma_f32_16x16x32_bf16 v[112:115], v[162:165], v[198:201], 0
	v_mfma_f32_16x16x32_bf16 v[100:103], v[146:149], v[206:209], 0
	v_mfma_f32_16x16x32_bf16 v[96:99], v[162:165], v[206:209], 0
	v_mfma_f32_16x16x32_bf16 v[84:87], v[146:149], v[214:217], 0
	v_mfma_f32_16x16x32_bf16 v[74:77], v[162:165], v[214:217], 0
	v_mfma_f32_16x16x32_bf16 v[132:135], v[152:155], v[190:193], v[132:135]
	v_mfma_f32_16x16x32_bf16 v[128:131], v[166:169], v[190:193], v[128:131]
	v_mfma_f32_16x16x32_bf16 v[116:119], v[152:155], v[202:205], v[116:119]
	v_mfma_f32_16x16x32_bf16 v[112:115], v[166:169], v[202:205], v[112:115]
	v_mfma_f32_16x16x32_bf16 v[100:103], v[152:155], v[210:213], v[100:103]
	v_mfma_f32_16x16x32_bf16 v[96:99], v[166:169], v[210:213], v[96:99]
	v_mfma_f32_16x16x32_bf16 v[84:87], v[152:155], v[218:221], v[84:87]
	v_mfma_f32_16x16x32_bf16 v[74:77], v[166:169], v[218:221], v[74:77]
	v_mfma_f32_16x16x32_bf16 v[124:127], v[170:173], v[186:189], 0
	v_mfma_f32_16x16x32_bf16 v[120:123], v[178:181], v[186:189], 0
	v_mfma_f32_16x16x32_bf16 v[108:111], v[170:173], v[198:201], 0
	v_mfma_f32_16x16x32_bf16 v[104:107], v[178:181], v[198:201], 0
	v_mfma_f32_16x16x32_bf16 v[92:95], v[170:173], v[206:209], 0
	v_mfma_f32_16x16x32_bf16 v[88:91], v[178:181], v[206:209], 0
	v_mfma_f32_16x16x32_bf16 v[70:73], v[170:173], v[214:217], 0
	v_mfma_f32_16x16x32_bf16 v[66:69], v[178:181], v[214:217], 0
	v_mfma_f32_16x16x32_bf16 v[124:127], v[174:177], v[190:193], v[124:127]
	v_mfma_f32_16x16x32_bf16 v[120:123], v[182:185], v[190:193], v[120:123]
	v_mfma_f32_16x16x32_bf16 v[108:111], v[174:177], v[202:205], v[108:111]
	v_mfma_f32_16x16x32_bf16 v[104:107], v[182:185], v[202:205], v[104:107]
	v_mfma_f32_16x16x32_bf16 v[92:95], v[174:177], v[210:213], v[92:95]
	v_mfma_f32_16x16x32_bf16 v[88:91], v[182:185], v[210:213], v[88:91]
	v_mfma_f32_16x16x32_bf16 v[70:73], v[174:177], v[218:221], v[70:73]
	v_mfma_f32_16x16x32_bf16 v[66:69], v[182:185], v[218:221], v[66:69]
	s_setprio 0
	s_barrier
	s_add_i32 s60, s60, s0
	v_lshl_add_u64 v[158:159], s[44:45], 0, v[138:139]
	s_mov_b32 m0, s60
	ds_read_b128 v[186:189], v161 offset:16384
	ds_read_b128 v[190:193], v161 offset:17408
	ds_read_b128 v[198:201], v161 offset:18432
	ds_read_b128 v[202:205], v161 offset:19456
	ds_read_b128 v[206:209], v161 offset:20480
	ds_read_b128 v[210:213], v161 offset:21504
	ds_read_b128 v[214:217], v161 offset:22528
	ds_read_b128 v[218:221], v161 offset:23552
	global_load_lds_dwordx4 v[158:159], off
	s_add_i32 m0, s60, 0x2000
	s_add_u32 s60, s44, 0x40000
	v_lshl_add_u64 v[194:195], s[44:45], 0, v[78:79]
	s_addc_u32 s61, s45, 0
	s_add_i32 s62, s62, s0
	global_load_lds_dwordx4 v[194:195], off
	v_lshl_add_u64 v[222:223], s[60:61], 0, v[138:139]
	s_mov_b32 m0, s62
	v_lshl_add_u64 v[224:225], s[46:47], 0, v[136:137]
	global_load_lds_dwordx4 v[222:223], off
	v_lshl_add_u64 v[222:223], s[60:61], 0, v[78:79]
	s_add_i32 m0, s62, 0x2000
	s_nop 0
	global_load_lds_dwordx4 v[222:223], off
	v_lshl_add_u64 v[222:223], s[46:47], 0, v[140:141]
	s_mov_b32 m0, s16
	s_nop 0
	global_load_lds_dwordx4 v[222:223], off
	s_mov_b32 m0, s17
	s_nop 0
	global_load_lds_dwordx4 v[224:225], off
	s_waitcnt vmcnt(8)
	s_waitcnt lgkmcnt(0)
	s_barrier
; #define PG8_STAGE(bufoff, gbase, voff) do { _Pragma("unroll") for (int _i = 0; _i < 2; ++_i) \
;         __builtin_amdgcn_global_load_lds((const unsigned*)((const char*)(gbase) + (voff)[_i]), (PG8_LAS unsigned*)(lds + (bufoff) + ldsw + _i * 8192), 16, 0, 0); } while (0)
; #define PG8_LDA(dst, b, h) do { _Pragma("unroll") for (int m = 0; m < 4; ++m) _Pragma("unroll") for (int k = 0; k < 2; ++k) dst[m][k] = *(const PG8_LAS bf16x8*)(lds + PG8_SA(b, h) + aoff + m * 2048 + k * 1024); } while (0)
; #define PG8_LDB(dst, b, h) do { _Pragma("unroll") for (int n = 0; n < 2; ++n) _Pragma("unroll") for (int k = 0; k < 2; ++k) dst[n][k] = *(const PG8_LAS bf16x8*)(lds + PG8_SB(b, h) + boff + n * 2048 + k * 1024); } while (0)
; #define PG8_MMA(ai, bj, At, Bt) do { __builtin_amdgcn_s_setprio(1); _Pragma("unroll") for (int m = 0; m < 4; ++m) _Pragma("unroll") for (int n = 0; n < 2; ++n) _Pragma("unroll") for (int k = 0; k < 2; ++k) \
;         acc[ai][bj][m][n] = __builtin_amdgcn_mfma_f32_16x16x32_bf16(Bt[n][k], At[m][k], acc[ai][bj][m][n], 0, 0, 0); __builtin_amdgcn_s_setprio(0); } while (0)
; #define PG8_WAIT_V(n) asm volatile("s_waitcnt vmcnt(" #n ")" ::: "memory")
; #define PG8_WAIT_L(n) asm volatile("s_waitcnt lgkmcnt(" #n ")" ::: "memory")
; #define PG8_BAR __builtin_amdgcn_s_barrier()
; #define PG8_SCHED __builtin_amdgcn_sched_barrier(0)
; template <class Epi, class Sched, bool ALIGN_EPI = false, bool SP2 = false>
; __device__ __forceinline__ void gemm_phase(PG8_LAS unsigned char* lds, const Gemm g, const Sched& S, const Epi& E) {
;     ...
;             PG8_WAIT_V(8); PG8_WAIT_L(0); PG8_BAR; PG8_MMA(1, 0, At, B0); PG8_MMA(1, 1, At, B1); PG8_BAR; PG8_SCHED;
;             PG8_LDB(B0, 1, 0); PG8_LDB(B1, 1, 1); PG8_SCHED; PG8_LDA(At, 1, 0); PG8_STAGE(PG8_SA(0, 1), a2 + hstepA, voffA);
;             PG8_WAIT_V(8); PG8_WAIT_L(0); PG8_BAR; PG8_MMA(0, 0, At, B0); PG8_MMA(0, 1, At, B1); PG8_BAR; PG8_SCHED;
	s_setprio 1
	s_waitcnt lgkmcnt(0)
	v_mfma_f32_16x16x32_bf16 v[62:65], v[146:149], v[186:189], 0
	v_mfma_f32_16x16x32_bf16 v[58:61], v[162:165], v[186:189], 0
	v_mfma_f32_16x16x32_bf16 v[46:49], v[146:149], v[198:201], 0
	v_mfma_f32_16x16x32_bf16 v[42:45], v[162:165], v[198:201], 0
	v_mfma_f32_16x16x32_bf16 v[30:33], v[146:149], v[206:209], 0
	v_mfma_f32_16x16x32_bf16 v[26:29], v[162:165], v[206:209], 0
	v_mfma_f32_16x16x32_bf16 v[14:17], v[146:149], v[214:217], 0
	v_mfma_f32_16x16x32_bf16 v[10:13], v[162:165], v[214:217], 0
	v_mfma_f32_16x16x32_bf16 v[62:65], v[152:155], v[190:193], v[62:65]
	v_mfma_f32_16x16x32_bf16 v[58:61], v[166:169], v[190:193], v[58:61]
	v_mfma_f32_16x16x32_bf16 v[46:49], v[152:155], v[202:205], v[46:49]
	v_mfma_f32_16x16x32_bf16 v[42:45], v[166:169], v[202:205], v[42:45]
	v_mfma_f32_16x16x32_bf16 v[30:33], v[152:155], v[210:213], v[30:33]
	v_mfma_f32_16x16x32_bf16 v[26:29], v[166:169], v[210:213], v[26:29]
	v_mfma_f32_16x16x32_bf16 v[14:17], v[152:155], v[218:221], v[14:17]
	v_mfma_f32_16x16x32_bf16 v[10:13], v[166:169], v[218:221], v[10:13]
	v_mfma_f32_16x16x32_bf16 v[54:57], v[170:173], v[186:189], 0
	v_mfma_f32_16x16x32_bf16 v[50:53], v[178:181], v[186:189], 0
	v_mfma_f32_16x16x32_bf16 v[38:41], v[170:173], v[198:201], 0
	v_mfma_f32_16x16x32_bf16 v[34:37], v[178:181], v[198:201], 0
	v_mfma_f32_16x16x32_bf16 v[22:25], v[170:173], v[206:209], 0
	v_mfma_f32_16x16x32_bf16 v[18:21], v[178:181], v[206:209], 0
	v_mfma_f32_16x16x32_bf16 v[6:9], v[170:173], v[214:217], 0
	v_mfma_f32_16x16x32_bf16 v[2:5], v[178:181], v[214:217], 0
	v_mfma_f32_16x16x32_bf16 v[54:57], v[174:177], v[190:193], v[54:57]
	v_mfma_f32_16x16x32_bf16 v[50:53], v[182:185], v[190:193], v[50:53]
	v_mfma_f32_16x16x32_bf16 v[38:41], v[174:177], v[202:205], v[38:41]
	v_mfma_f32_16x16x32_bf16 v[34:37], v[182:185], v[202:205], v[34:37]
	v_mfma_f32_16x16x32_bf16 v[22:25], v[174:177], v[210:213], v[22:25]
	v_mfma_f32_16x16x32_bf16 v[18:21], v[182:185], v[210:213], v[18:21]
	v_mfma_f32_16x16x32_bf16 v[6:9], v[174:177], v[218:221], v[6:9]
	v_mfma_f32_16x16x32_bf16 v[2:5], v[182:185], v[218:221], v[2:5]
	s_setprio 0
	s_barrier
	s_add_i32 s60, 0, 0x18000
	v_add_u32_e32 v150, s60, v151
	s_add_i32 s61, 0, 0x1c000
	ds_read_b128 v[146:149], v150
	ds_read_b128 v[152:155], v150 offset:1024
	ds_read_b128 v[162:165], v150 offset:2048
	ds_read_b128 v[166:169], v150 offset:3072
	v_add_u32_e32 v150, s61, v151
	ds_read_b128 v[170:173], v150
	ds_read_b128 v[174:177], v150 offset:1024
	ds_read_b128 v[178:181], v150 offset:2048
	ds_read_b128 v[182:185], v150 offset:3072
	s_add_u32 s46, s46, 0x40000
	s_addc_u32 s47, s47, 0
	s_mov_b32 m0, s37
	v_lshl_add_u64 v[226:227], s[46:47], 0, v[140:141]
	ds_read_b128 v[186:189], v161 offset:32768
	ds_read_b128 v[190:193], v161 offset:33792
	ds_read_b128 v[198:201], v161 offset:34816
	ds_read_b128 v[202:205], v161 offset:35840
	ds_read_b128 v[206:209], v161 offset:36864
	ds_read_b128 v[210:213], v161 offset:37888
	ds_read_b128 v[214:217], v161 offset:38912
	ds_read_b128 v[218:221], v161 offset:39936
	global_load_lds_dwordx4 v[226:227], off
	v_lshl_add_u64 v[226:227], s[46:47], 0, v[136:137]
	s_mov_b32 m0, s48
	s_nop 0
	global_load_lds_dwordx4 v[226:227], off
	s_waitcnt vmcnt(8)
	s_waitcnt lgkmcnt(0)
	s_barrier
	s_setprio 1
	s_waitcnt lgkmcnt(0)
	v_mfma_f32_16x16x32_bf16 v[132:135], v[146:149], v[186:189], v[132:135]
	v_mfma_f32_16x16x32_bf16 v[128:131], v[162:165], v[186:189], v[128:131]
	v_mfma_f32_16x16x32_bf16 v[116:119], v[146:149], v[198:201], v[116:119]
	v_mfma_f32_16x16x32_bf16 v[112:115], v[162:165], v[198:201], v[112:115]
	v_mfma_f32_16x16x32_bf16 v[100:103], v[146:149], v[206:209], v[100:103]
	v_mfma_f32_16x16x32_bf16 v[96:99], v[162:165], v[206:209], v[96:99]
	v_mfma_f32_16x16x32_bf16 v[84:87], v[146:149], v[214:217], v[84:87]
	v_mfma_f32_16x16x32_bf16 v[74:77], v[162:165], v[214:217], v[74:77]
	v_mfma_f32_16x16x32_bf16 v[132:135], v[152:155], v[190:193], v[132:135]
	v_mfma_f32_16x16x32_bf16 v[128:131], v[166:169], v[190:193], v[128:131]
	v_mfma_f32_16x16x32_bf16 v[116:119], v[152:155], v[202:205], v[116:119]
	v_mfma_f32_16x16x32_bf16 v[112:115], v[166:169], v[202:205], v[112:115]
	v_mfma_f32_16x16x32_bf16 v[100:103], v[152:155], v[210:213], v[100:103]
	v_mfma_f32_16x16x32_bf16 v[96:99], v[166:169], v[210:213], v[96:99]
	v_mfma_f32_16x16x32_bf16 v[84:87], v[152:155], v[218:221], v[84:87]
	v_mfma_f32_16x16x32_bf16 v[74:77], v[166:169], v[218:221], v[74:77]
	v_mfma_f32_16x16x32_bf16 v[124:127], v[170:173], v[186:189], v[124:127]
	v_mfma_f32_16x16x32_bf16 v[120:123], v[178:181], v[186:189], v[120:123]
	v_mfma_f32_16x16x32_bf16 v[108:111], v[170:173], v[198:201], v[108:111]
	v_mfma_f32_16x16x32_bf16 v[104:107], v[178:181], v[198:201], v[104:107]
	v_mfma_f32_16x16x32_bf16 v[92:95], v[170:173], v[206:209], v[92:95]
	v_mfma_f32_16x16x32_bf16 v[88:91], v[178:181], v[206:209], v[88:91]
	v_mfma_f32_16x16x32_bf16 v[70:73], v[170:173], v[214:217], v[70:73]
	v_mfma_f32_16x16x32_bf16 v[66:69], v[178:181], v[214:217], v[66:69]
	v_mfma_f32_16x16x32_bf16 v[124:127], v[174:177], v[190:193], v[124:127]
	v_mfma_f32_16x16x32_bf16 v[120:123], v[182:185], v[190:193], v[120:123]
	v_mfma_f32_16x16x32_bf16 v[108:111], v[174:177], v[202:205], v[108:111]
	v_mfma_f32_16x16x32_bf16 v[104:107], v[182:185], v[202:205], v[104:107]
	v_mfma_f32_16x16x32_bf16 v[92:95], v[174:177], v[210:213], v[92:95]
	v_mfma_f32_16x16x32_bf16 v[88:91], v[182:185], v[210:213], v[88:91]
	v_mfma_f32_16x16x32_bf16 v[70:73], v[174:177], v[218:221], v[70:73]
	v_mfma_f32_16x16x32_bf16 v[66:69], v[182:185], v[218:221], v[66:69]
	s_setprio 0
	s_barrier
; #define PG8_STAGE(bufoff, gbase, voff) do { _Pragma("unroll") for (int _i = 0; _i < 2; ++_i) \
;         __builtin_amdgcn_global_load_lds((const unsigned*)((const char*)(gbase) + (voff)[_i]), (PG8_LAS unsigned*)(lds + (bufoff) + ldsw + _i * 8192), 16, 0, 0); } while (0)
; #define PG8_LDA(dst, b, h) do { _Pragma("unroll") for (int m = 0; m < 4; ++m) _Pragma("unroll") for (int k = 0; k < 2; ++k) dst[m][k] = *(const PG8_LAS bf16x8*)(lds + PG8_SA(b, h) + aoff + m * 2048 + k * 1024); } while (0)
; #define PG8_MMA(ai, bj, At, Bt) do { __builtin_amdgcn_s_setprio(1); _Pragma("unroll") for (int m = 0; m < 4; ++m) _Pragma("unroll") for (int n = 0; n < 2; ++n) _Pragma("unroll") for (int k = 0; k < 2; ++k) \
;         acc[ai][bj][m][n] = __builtin_amdgcn_mfma_f32_16x16x32_bf16(Bt[n][k], At[m][k], acc[ai][bj][m][n], 0, 0, 0); __builtin_amdgcn_s_setprio(0); } while (0)
; #define PG8_WAIT_V(n) asm volatile("s_waitcnt vmcnt(" #n ")" ::: "memory")
; #define PG8_WAIT_L(n) asm volatile("s_waitcnt lgkmcnt(" #n ")" ::: "memory")
; #define PG8_BAR __builtin_amdgcn_s_barrier()
; #define PG8_SCHED __builtin_amdgcn_sched_barrier(0)
; template <class Epi, class Sched, bool ALIGN_EPI = false, bool SP2 = false>
; __device__ __forceinline__ void gemm_phase(PG8_LAS unsigned char* lds, const Gemm g, const Sched& S, const Epi& E) {
;     ...
;         for (int t = 0; t < nt; t += 2) {
;     ...
;             PG8_LDA(At, 1, 1); PG8_STAGE(PG8_SB(1, 0), b3, voffB); PG8_STAGE(PG8_SB(1, 1), b3 + hstep, voffB); PG8_STAGE(PG8_SA(1, 0), a3, voffA);
;             PG8_WAIT_V(8); PG8_WAIT_L(0); PG8_BAR; PG8_MMA(1, 0, At, B0); PG8_MMA(1, 1, At, B1); PG8_BAR; PG8_SCHED;
	s_add_i32 s46, s60, s0
	v_lshl_add_u64 v[158:159], v[158:159], 0, s[26:27]
	s_mov_b32 m0, s46
	ds_read_b128 v[186:189], v161 offset:49152
	ds_read_b128 v[190:193], v161 offset:50176
	ds_read_b128 v[198:201], v161 offset:51200
	ds_read_b128 v[202:205], v161 offset:52224
	ds_read_b128 v[206:209], v161 offset:53248
	ds_read_b128 v[210:213], v161 offset:54272
	ds_read_b128 v[214:217], v161 offset:55296
	ds_read_b128 v[218:221], v161 offset:56320
	global_load_lds_dwordx4 v[158:159], off
	s_add_i32 m0, s46, 0x2000
	s_add_u32 s44, s44, 0x40080
	v_lshl_add_u64 v[158:159], v[194:195], 0, s[26:27]
	s_addc_u32 s45, s45, 0
	s_add_i32 s46, s61, s0
	global_load_lds_dwordx4 v[158:159], off
	v_lshl_add_u64 v[158:159], s[44:45], 0, v[138:139]
	s_mov_b32 m0, s46
	s_nop 0
	global_load_lds_dwordx4 v[158:159], off
	v_lshl_add_u64 v[158:159], s[44:45], 0, v[78:79]
	s_add_i32 m0, s46, 0x2000
	s_nop 0
	global_load_lds_dwordx4 v[158:159], off
	v_lshl_add_u64 v[158:159], v[222:223], 0, s[26:27]
	s_mov_b32 m0, s49
	s_nop 0
	global_load_lds_dwordx4 v[158:159], off
	v_lshl_add_u64 v[158:159], v[224:225], 0, s[26:27]
	s_mov_b32 m0, s53
	s_nop 0
	global_load_lds_dwordx4 v[158:159], off
	s_waitcnt vmcnt(8)
	s_waitcnt lgkmcnt(0)
	s_barrier
	s_setprio 1
	s_waitcnt lgkmcnt(0)
	v_mfma_f32_16x16x32_bf16 v[62:65], v[146:149], v[186:189], v[62:65]
	v_mfma_f32_16x16x32_bf16 v[58:61], v[162:165], v[186:189], v[58:61]
	v_mfma_f32_16x16x32_bf16 v[46:49], v[146:149], v[198:201], v[46:49]
	v_mfma_f32_16x16x32_bf16 v[42:45], v[162:165], v[198:201], v[42:45]
	v_mfma_f32_16x16x32_bf16 v[30:33], v[146:149], v[206:209], v[30:33]
	v_mfma_f32_16x16x32_bf16 v[26:29], v[162:165], v[206:209], v[26:29]
	v_mfma_f32_16x16x32_bf16 v[14:17], v[146:149], v[214:217], v[14:17]
	v_mfma_f32_16x16x32_bf16 v[10:13], v[162:165], v[214:217], v[10:13]
	v_mfma_f32_16x16x32_bf16 v[62:65], v[152:155], v[190:193], v[62:65]
	v_mfma_f32_16x16x32_bf16 v[58:61], v[166:169], v[190:193], v[58:61]
	v_mfma_f32_16x16x32_bf16 v[46:49], v[152:155], v[202:205], v[46:49]
	v_mfma_f32_16x16x32_bf16 v[42:45], v[166:169], v[202:205], v[42:45]
	v_mfma_f32_16x16x32_bf16 v[30:33], v[152:155], v[210:213], v[30:33]
	v_mfma_f32_16x16x32_bf16 v[26:29], v[166:169], v[210:213], v[26:29]
	v_mfma_f32_16x16x32_bf16 v[14:17], v[152:155], v[218:221], v[14:17]
	v_mfma_f32_16x16x32_bf16 v[10:13], v[166:169], v[218:221], v[10:13]
	v_mfma_f32_16x16x32_bf16 v[54:57], v[170:173], v[186:189], v[54:57]
	v_mfma_f32_16x16x32_bf16 v[50:53], v[178:181], v[186:189], v[50:53]
	v_mfma_f32_16x16x32_bf16 v[38:41], v[170:173], v[198:201], v[38:41]
	v_mfma_f32_16x16x32_bf16 v[34:37], v[178:181], v[198:201], v[34:37]
	v_mfma_f32_16x16x32_bf16 v[22:25], v[170:173], v[206:209], v[22:25]
	v_mfma_f32_16x16x32_bf16 v[18:21], v[178:181], v[206:209], v[18:21]
	v_mfma_f32_16x16x32_bf16 v[6:9], v[170:173], v[214:217], v[6:9]
	v_mfma_f32_16x16x32_bf16 v[2:5], v[178:181], v[214:217], v[2:5]
	v_mfma_f32_16x16x32_bf16 v[54:57], v[174:177], v[190:193], v[54:57]
	v_mfma_f32_16x16x32_bf16 v[50:53], v[182:185], v[190:193], v[50:53]
	v_mfma_f32_16x16x32_bf16 v[38:41], v[174:177], v[202:205], v[38:41]
	v_mfma_f32_16x16x32_bf16 v[34:37], v[182:185], v[202:205], v[34:37]
	v_mfma_f32_16x16x32_bf16 v[22:25], v[174:177], v[210:213], v[22:25]
	v_mfma_f32_16x16x32_bf16 v[18:21], v[182:185], v[210:213], v[18:21]
	v_mfma_f32_16x16x32_bf16 v[6:9], v[174:177], v[218:221], v[6:9]
	v_mfma_f32_16x16x32_bf16 v[2:5], v[182:185], v[218:221], v[2:5]
	s_setprio 0
	s_barrier
	s_add_i32 s59, s59, 2
	s_add_u32 s42, s42, 0x100
	s_addc_u32 s43, s43, 0
	s_add_u32 s57, s57, 0x100
	s_addc_u32 s58, s58, 0
	s_cmp_gt_u32 s59, 13
